# layer-0 ctx split-K mlp-out units deferred past seam 5 to overlap the latent row work of phase 6; one extra grid barrier before the ctx rows
# baseline (speedup 1.0000x reference)
; template <class Epi, class Sched, bool ALIGN_EPI = false, bool SP2 = false>
; __device__ __forceinline__ void gemm_phase(PG8_LAS unsigned char* lds, const Gemm g, const Sched& S, const Epi& E) {
;     const int tid = threadIdx.x, wid = __builtin_amdgcn_readfirstlane(tid >> 6), lane = tid & 63, wr = wid >> 2, wc = wid & 3, fr = lane & 15, fq = lane >> 4;
;     const int K = g.K, nt = K / BK;
;     unsigned voffA[2], voffB[2];
; #pragma unroll
;     for (int i = 0; i < 2; ++i) { int R, C; stage_rc(tid * 16 + i * 8192, R, C); const int Rb = Epi::PERM2 ? (128 * ((R >> 6) & 1) + 64 * ((R >> 5) & 1) + 32 * ((R >> 4) & 1) + 8 * ((R & 15) >> 2) + (R & 3)) : (Epi::PERM ? ((R & ~31) + perm32(R & 31)) : R);
;         voffA[i] = (unsigned)(R * g.lda + C) * 2u; voffB[i] = (unsigned)(Rb * g.ldb + C) * 2u; }
;     const size_t kstep = (size_t)(BK * 2);
;     const size_t hstepA = (size_t)HALF * g.lda * 2, hstepB = Epi::PERM2 ? (size_t)4 * g.ldb * 2 : (size_t)HALF * g.ldb * 2;
;     const size_t tstepA = 2 * hstepA, tstepB = (size_t)2 * HALF * g.ldb * 2;
;     const unsigned ldsw = (unsigned)wid * 1024u;
;     const int aoff = lds_byte(wr * 64 + fr, fq * 8), boff = lds_byte(wc * 32 + fr, fq * 8);
; __global__ void __launch_bounds__(NTHR, 2) fwd_megakernel(KArgs a) {
;     ...
;     if (IN(5)) {
;         pg8::Gemm g{HB, (const pg8::bf16_t*)(ws + WS_WOUT0), MLAT, DM, FF, FF, FF, 1, 1 << 20, 0, 0}; pg8::StaticOrder S; S.init(MLAT, DM, gridDim.x, blockIdx.x);
;         pg8::EpiStore<0> E{AY, DM, nullptr};
;         pg8::gemm_phase<pg8::EpiStore<0>, pg8::StaticOrder, true, true>(lds, g, S, E);
.LBB0_460:
	s_mov_b32 s98, 0
	s_cmp_lt_i32 s92, 6
	s_cselect_b64 s[2:3], -1, 0
	s_and_b64 s[4:5], s[2:3], s[0:1]
	s_andn2_b64 vcc, exec, s[4:5]
	s_cbranch_vccnz .LBB0_515
	v_lshrrev_b32_e32 v4, 5, v0
	v_lshrrev_b32_e32 v6, 1, v0
	v_lshlrev_b32_e32 v2, 4, v0
	v_and_b32_e32 v1, 32, v0
	v_and_b32_e32 v4, 4, v4
	v_bfe_u32 v5, v0, 2, 2
	v_and_b32_e32 v151, 24, v6
	v_bfe_u32 v149, v0, 2, 4
	v_bitop3_b32 v1, v2, v1, 48 bitop3:0x6c
	v_and_b32_e32 v148, 64, v0
	v_or3_b32 v4, v4, v5, v151
	v_lshrrev_b32_e32 v5, 3, v0
	v_or_b32_e32 v150, 0x2000, v2
	v_or_b32_e32 v3, v1, v148
	v_and_or_b32 v6, v5, 48, v149
	v_and_or_b32 v5, v5, 32, v4
	v_lshrrev_b32_e32 v2, 7, v150
	s_movk_i32 s0, 0x70
	v_lshl_or_b32 v132, v5, 13, v3
	v_and_or_b32 v5, v2, s0, v149
	s_movk_i32 s0, 0x60
	v_and_or_b32 v2, v2, s0, v4
	s_add_u32 s66, s58, 0x1a00000
	v_lshl_or_b32 v130, v6, 13, v3
	v_lshl_or_b32 v134, v5, 13, v3
	v_lshl_or_b32 v136, v2, 13, v3
	v_lshlrev_b32_e32 v2, 6, v0
	v_lshlrev_b32_e32 v3, 2, v0
	s_addc_u32 s67, s59, 0
	v_lshlrev_b32_e32 v153, 1, v151
	v_and_b32_e32 v2, 0x3c0, v2
	v_and_b32_e32 v3, 32, v3
	v_readfirstlane_b32 s2, v0
	v_and_b32_e32 v152, 15, v0
	s_cmpk_gt_i32 s14, 0xff
	v_bitop3_b32 v154, v153, v3, v2 bitop3:0x36
	s_cbranch_scc1 .LBB0_487
	s_ashr_i32 s68, s14, 31
	s_lshr_b32 s0, s68, 29
	s_add_i32 s3, s14, s0
	s_and_b32 s0, s3, -8
	s_sub_i32 s7, s14, s0
	s_cmp_gt_i32 s7, -1
	s_cbranch_scc0 .LBB0_464
	s_lshl_b32 s6, s7, 5
	s_cbranch_execz .LBB0_465
	s_branch .LBB0_466

; template <class Epi, class Sched, bool ALIGN_EPI = false, bool SP2 = false>
; __device__ __forceinline__ void gemm_phase(PG8_LAS unsigned char* lds, const Gemm g, const Sched& S, const Epi& E) {
;     const int tid = threadIdx.x, wid = __builtin_amdgcn_readfirstlane(tid >> 6), lane = tid & 63, wr = wid >> 2, wc = wid & 3, fr = lane & 15, fq = lane >> 4;
;     const int K = g.K, nt = K / BK;
;     unsigned voffA[2], voffB[2];
; #pragma unroll
;     for (int i = 0; i < 2; ++i) { int R, C; stage_rc(tid * 16 + i * 8192, R, C); const int Rb = Epi::PERM2 ? (128 * ((R >> 6) & 1) + 64 * ((R >> 5) & 1) + 32 * ((R >> 4) & 1) + 8 * ((R & 15) >> 2) + (R & 3)) : (Epi::PERM ? ((R & ~31) + perm32(R & 31)) : R);
;         voffA[i] = (unsigned)(R * g.lda + C) * 2u; voffB[i] = (unsigned)(Rb * g.ldb + C) * 2u; }
;     const size_t kstep = (size_t)(BK * 2);
;     const size_t hstepA = (size_t)HALF * g.lda * 2, hstepB = Epi::PERM2 ? (size_t)4 * g.ldb * 2 : (size_t)HALF * g.ldb * 2;
;     const size_t tstepA = 2 * hstepA, tstepB = (size_t)2 * HALF * g.ldb * 2;
;     const unsigned ldsw = (unsigned)wid * 1024u;
;     const int aoff = lds_byte(wr * 64 + fr, fq * 8), boff = lds_byte(wc * 32 + fr, fq * 8);
; __global__ void __launch_bounds__(NTHR, 2) fwd_megakernel(KArgs a) {
;     ...
;         pg8::Gemm g2{HB + (size_t)MLAT * FF, (const pg8::bf16_t*)(ws + WS_WOUT0), MCTX, DM * KSPLIT, FF / KSPLIT, FF, FF, 4, 4, (size_t)(FF / KSPLIT) * 2, (size_t)(FF / KSPLIT) * 2};
;         pg8::StaticOrder S2; S2.init(MCTX, DM * KSPLIT, gridDim.x, blockIdx.x);
;         pg8::EpiPart E2{a.out};
;         pg8::gemm_phase<pg8::EpiPart, pg8::StaticOrder, true, true>(lds, g2, S2, E2);
.LBB0_487:
	s_mov_b32 s98, 1
	s_branch .LBB0_515
.Lfa_ctx:
	s_cmp_gt_i32 s14, 63
	s_cbranch_scc1 .Lfa_p6r
	v_lshrrev_b32_e32 v4, 5, v0
	v_lshrrev_b32_e32 v6, 1, v0
	v_lshlrev_b32_e32 v2, 4, v0
	v_and_b32_e32 v1, 32, v0
	v_and_b32_e32 v4, 4, v4
	v_bfe_u32 v5, v0, 2, 2
	v_and_b32_e32 v151, 24, v6
	v_bfe_u32 v149, v0, 2, 4
	v_bitop3_b32 v1, v2, v1, 48 bitop3:0x6c
	v_and_b32_e32 v148, 64, v0
	v_or3_b32 v4, v4, v5, v151
	v_lshrrev_b32_e32 v5, 3, v0
	v_or_b32_e32 v150, 0x2000, v2
	v_or_b32_e32 v3, v1, v148
	v_and_or_b32 v6, v5, 48, v149
	v_and_or_b32 v5, v5, 32, v4
	v_lshrrev_b32_e32 v2, 7, v150
	s_movk_i32 s0, 0x70
	v_lshl_or_b32 v132, v5, 13, v3
	v_and_or_b32 v5, v2, s0, v149
	s_movk_i32 s0, 0x60
	v_and_or_b32 v2, v2, s0, v4
	s_add_u32 s66, s58, 0x1a00000
	v_lshl_or_b32 v130, v6, 13, v3
	v_lshl_or_b32 v134, v5, 13, v3
	v_lshl_or_b32 v136, v2, 13, v3
	v_lshlrev_b32_e32 v2, 6, v0
	v_lshlrev_b32_e32 v3, 2, v0
	s_addc_u32 s67, s59, 0
	v_lshlrev_b32_e32 v153, 1, v151
	v_and_b32_e32 v2, 0x3c0, v2
	v_and_b32_e32 v3, 32, v3
	v_readfirstlane_b32 s2, v0
	v_and_b32_e32 v152, 15, v0
	v_bitop3_b32 v154, v153, v3, v2 bitop3:0x36
	s_ashr_i32 s68, s14, 31
	s_lshr_b32 s0, s68, 29
	s_add_i32 s3, s14, s0
	s_and_b32 s0, s3, -8
	s_sub_i32 s6, s14, s0
	s_cmp_gt_i32 s6, -1
	s_cbranch_scc0 .LBB0_490
	s_lshl_b32 s7, s6, 3
	s_cbranch_execz .LBB0_491
	s_branch .LBB0_492

; #define SEAM(k) do { if (IN(k) && IN((k) + 1)) xcd_barrier(bar); } while (0)
; __global__ void __launch_bounds__(NTHR, 2) fwd_megakernel(KArgs a) {
;     ...
;     if (IN(6)) { phase_rows<false, true, true>(a, 0, MLAT, 8, mods0, 5, a.g_mlp_post, mods1, 0, a.g_mix_pre + DM, lane, wave); phase_rows<false, true, true>(a, MLAT, MCTX, 2, mods0, 5, a.g_mlp_post, mods1, 0, a.g_mix_pre + DM, lane, wave); } SEAM(6);
.Lfa_p6r:
	v_readlane_b32 s0, v254, 11
	v_readlane_b32 s1, v254, 12
	v_readlane_b32 s8, v254, 13
	v_readlane_b32 s15, v254, 14
	v_readlane_b32 s30, v254, 15
	v_readlane_b32 s31, v254, 16
	v_readlane_b32 s36, v254, 17
	v_readlane_b32 s37, v254, 18
	v_readlane_b32 s38, v254, 19
	v_readlane_b32 s39, v254, 20
	v_readlane_b32 s40, v254, 21
	v_readlane_b32 s41, v254, 22
	s_branch .Lfa_p6

; #define SEAM(k) do { if (IN(k) && IN((k) + 1)) xcd_barrier(bar); } while (0)
; __global__ void __launch_bounds__(NTHR, 2) fwd_megakernel(KArgs a) {
;     ...
;         pg8::gemm_phase<pg8::EpiPart, pg8::StaticOrder, true, true>(lds, g2, S2, E2);
;     } SEAM(5);
;     if (IN(6)) { phase_rows<false, true, true>(a, 0, MLAT, 8, mods0, 5, a.g_mlp_post, mods1, 0, a.g_mix_pre + DM, lane, wave); phase_rows<false, true, true>(a, MLAT, MCTX, 2, mods0, 5, a.g_mlp_post, mods1, 0, a.g_mix_pre + DM, lane, wave); } SEAM(6);
.LBB0_569:
	s_cmp_eq_u32 s98, 1
	s_cbranch_scc0 .Lfa_p6
	s_mov_b32 s98, 0
	v_writelane_b32 v254, s0, 11
	v_writelane_b32 v254, s1, 12
	v_writelane_b32 v254, s8, 13
	v_writelane_b32 v254, s15, 14
	v_writelane_b32 v254, s30, 15
	v_writelane_b32 v254, s31, 16
	v_writelane_b32 v254, s36, 17
	v_writelane_b32 v254, s37, 18
	v_writelane_b32 v254, s38, 19
	v_writelane_b32 v254, s39, 20
	v_writelane_b32 v254, s40, 21
	v_writelane_b32 v254, s41, 22
	s_branch .Lfa_ctx

; __device__ __forceinline__ unsigned xb_ld(unsigned* p)              { return __hip_atomic_load(p, __ATOMIC_RELAXED, __HIP_MEMORY_SCOPE_AGENT); }
; __device__ __forceinline__ unsigned xb_add(unsigned* p, unsigned v) { return __hip_atomic_fetch_add(p, v, __ATOMIC_RELAXED, __HIP_MEMORY_SCOPE_AGENT); }
; #define XB_SPIN(cond, bar) do { unsigned _sp = 0; while (cond) { __builtin_amdgcn_s_sleep(1); \
;     if ((++_sp & 255u) == 0u) { if (xb_ld(&(bar)[XB_TMO])) break; if (_sp > XB_SPIN_CAP) { atomicAdd(&(bar)[XB_TMO], 1u); break; } } } } while (0)
; __device__ __forceinline__ void xcd_barrier(const XcdBarrier& b) {
;     asm volatile("s_waitcnt vmcnt(0)" ::: "memory");
;     __syncthreads();
;     if (threadIdx.x == 0) {
;         unsigned* bar = b.bar;
;         __builtin_amdgcn_s_waitcnt(0);
;         unsigned nloc = b.st[0], nx = b.st[1];
;         if (nloc == 0u) { xcd_barrier_complete(bar, b.x, nloc, nx); b.st[0] = nloc; b.st[1] = nx; }
;         const unsigned old = xb_add(&bar[XB_XSUB(b.x)], 1u);
;         const unsigned gen = old / nloc;
;         if (old + 1u == (gen + 1u) * nloc) {
;             __builtin_amdgcn_fence(__ATOMIC_RELEASE, "agent");
;             asm volatile("s_waitcnt vmcnt(0)" ::: "memory");
;             const unsigned og = xb_add(&bar[XB_TOP], 1u);
;             const unsigned tg = og / nx;
;             if (og + 1u == (tg + 1u) * nx) xb_add(&bar[XB_TOPGEN], 1u);
;             else XB_SPIN(xb_ld(&bar[XB_TOPGEN]) == tg, bar);
;             __builtin_amdgcn_fence(__ATOMIC_ACQUIRE, "agent");
;             xb_add(&bar[XB_XGEN(b.x)], 1u);
;             asm volatile("s_waitcnt vmcnt(0)" ::: "memory");
;         } else {
;             XB_SPIN(xb_ld(&bar[XB_XGEN(b.x)]) == gen, bar);
;             __builtin_amdgcn_fence(__ATOMIC_ACQUIRE, "agent");
;             asm volatile("s_waitcnt vmcnt(0)" ::: "memory");
;         }
;     }
.LBB0_591:
	v_writelane_b32 v254, s2, 23
	v_writelane_b32 v254, s3, 24
	v_writelane_b32 v254, s4, 25
	v_writelane_b32 v254, s5, 26
	v_writelane_b32 v254, s8, 27
	v_writelane_b32 v254, s30, 28
	v_writelane_b32 v254, s31, 29
	v_writelane_b32 v254, s36, 30
	v_writelane_b32 v254, s37, 31
	v_writelane_b32 v254, s38, 32
	v_writelane_b32 v254, s39, 33
	v_writelane_b32 v254, s40, 34
	v_writelane_b32 v254, s41, 35
	s_waitcnt vmcnt(0)
	s_waitcnt vmcnt(0)
	s_barrier
	s_mov_b64 s[2:3], exec
	v_readlane_b32 s4, v254, 4
	v_readlane_b32 s5, v254, 5
	s_and_b64 s[4:5], s[2:3], s[4:5]
	s_mov_b64 exec, s[4:5]
	s_cbranch_execz .Lfb_568
	s_add_i32 s4, 0, 0x20040
	v_mov_b32_e32 v1, s4
	s_waitcnt vmcnt(0) expcnt(0) lgkmcnt(0)
	ds_read_b32 v3, v1
	s_add_i32 s4, 0, 0x20044
	v_mov_b32_e32 v1, s4
	ds_read_b32 v1, v1
	s_waitcnt lgkmcnt(1)
	v_cmp_ne_u32_e32 vcc, 0, v3
	s_cbranch_vccnz .Lfb_532
	v_readlane_b32 s4, v254, 0
	s_mul_i32 s12, s95, s4
	s_add_u32 s4, s58, 0x4200
	s_addc_u32 s5, s59, 0
	s_add_u32 s6, s58, 0x4400
	s_addc_u32 s7, s59, 0
	s_add_u32 s8, s58, 0x4500
	s_addc_u32 s9, s59, 0
	s_add_u32 s24, s58, 0x4600
	s_addc_u32 s25, s59, 0
	s_add_u32 s30, s58, 0x4700
	s_addc_u32 s31, s59, 0
	s_add_u32 s36, s58, 0x4800
	s_addc_u32 s37, s59, 0
	s_add_u32 s38, s58, 0x4900
	s_addc_u32 s39, s59, 0
	s_add_u32 s40, s58, 0x4a00
	s_addc_u32 s41, s59, 0
	s_add_u32 s42, s58, 0x4b00
	s_addc_u32 s43, s59, 0
	s_add_u32 s44, s58, 0x4c00
	s_addc_u32 s45, s59, 0
	s_add_u32 s46, s58, 0x4d00
	s_addc_u32 s47, s59, 0
	s_add_u32 s52, s58, 0x4e00
	s_addc_u32 s53, s59, 0
	s_add_u32 s54, s58, 0x4f00
	s_addc_u32 s55, s59, 0
	s_add_u32 s64, s58, 0x5000
	s_addc_u32 s65, s59, 0
	s_add_u32 s66, s58, 0x5100
	s_addc_u32 s67, s59, 0
	s_add_u32 s68, s58, 0x5200
	s_addc_u32 s69, s59, 0
	s_add_u32 s70, s58, 0x5300
	s_mul_i32 s12, s12, s94
	s_addc_u32 s71, s59, 0
	s_mov_b32 s13, 1
	v_mov_b32_e32 v17, 0
	s_branch .Lfb_520

; template <bool FIRST, bool HAS_NEXT, bool CTXSPLIT = false>
; __device__ __forceinline__ void phase_rows(const KArgs& a, int row_begin, int nrows, int CH, const float* mods_cur, int gate_ch, const float* g_post, const float* mods_nxt, int sh_ch, const float* g_pre, int lane, int wave) {
;     ...
;     const int gw = blockIdx.x * NWAVES + wave, NGW = gridDim.x * NWAVES;
;     ...
;     for (int ch = gw; ch < nrows / CH; ch += NGW) {
;         const int r0 = row_begin + ch * CH; const int ms = r0 < MLAT ? r0 / SEQ : 2;
;         f32x4 gg[4], gs[4], sh[4];
; #pragma unroll
;         for (int j = 0; j < 4; ++j) { const int col = RCOL(j);
;             gg[j] = *(const f32x4*)(mods_cur + ms * MODW + gate_ch * DM + col) * *(const f32x4*)(g_post + col);
;             if (HAS_NEXT) { gs[j] = *(const f32x4*)(g_pre + col) * (1.0f + *(const f32x4*)(mods_nxt + ms * MODW + (sh_ch + 1) * DM + col)); sh[j] = *(const f32x4*)(mods_nxt + ms * MODW + sh_ch * DM + col); }
;         }
; __device__ __forceinline__ void xcd_barrier(const XcdBarrier& b) {
;     ...
;     __syncthreads();
; }
.Lfb_568:
	s_or_b64 exec, exec, s[2:3]
	s_waitcnt lgkmcnt(0)
	s_barrier
	v_readlane_b32 s2, v254, 23
	v_readlane_b32 s3, v254, 24
	v_readlane_b32 s4, v254, 25
	v_readlane_b32 s5, v254, 26
	v_readlane_b32 s8, v254, 27
	v_readlane_b32 s30, v254, 28
	v_readlane_b32 s31, v254, 29
	v_readlane_b32 s36, v254, 30
	v_readlane_b32 s37, v254, 31
	v_readlane_b32 s38, v254, 32
	v_readlane_b32 s39, v254, 33
	v_readlane_b32 s40, v254, 34
	v_readlane_b32 s41, v254, 35
	v_readlane_b32 s92, v254, 7
	s_cmpk_gt_i32 s86, 0xff
	v_readlane_b32 s93, v254, 8
	v_readlane_b32 s94, v254, 9
	v_readlane_b32 s95, v254, 10
	s_cbranch_scc1 .LBB0_612
	v_mbcnt_lo_u32_b32 v1, -1, 0
	v_mbcnt_hi_u32_b32 v3, -1, v1
	v_and_b32_e32 v1, 64, v3
	v_add_u32_e32 v4, 64, v1
	v_xor_b32_e32 v1, 1, v3
	v_cmp_lt_i32_e32 vcc, v1, v4
	v_xor_b32_e32 v5, 2, v3
	v_lshlrev_b32_e32 v130, 3, v198
	v_cndmask_b32_e32 v1, v3, v1, vcc
	v_cmp_lt_i32_e32 vcc, v5, v4
	v_mov_b32_e32 v133, 0
	v_lshlrev_b32_e32 v132, 5, v198
	v_cndmask_b32_e32 v5, v3, v5, vcc
	v_lshlrev_b32_e32 v131, 2, v5
	v_xor_b32_e32 v5, 4, v3
	v_cmp_lt_i32_e32 vcc, v5, v4
	v_or_b32_e32 v2, 0x200, v130
	v_lshl_add_u64 v[134:135], s[18:19], 0, v[132:133]
	v_cndmask_b32_e32 v5, v3, v5, vcc
	v_lshlrev_b32_e32 v160, 2, v5
	v_xor_b32_e32 v5, 8, v3
	v_cmp_lt_i32_e32 vcc, v5, v4
	v_lshl_add_u64 v[136:137], s[2:3], 0, v[132:133]
	v_lshlrev_b32_e32 v132, 2, v2
	v_cndmask_b32_e32 v5, v3, v5, vcc
	v_lshlrev_b32_e32 v161, 2, v5
	v_xor_b32_e32 v5, 16, v3
	v_cmp_lt_i32_e32 vcc, v5, v4
	v_lshl_add_u64 v[138:139], s[2:3], 0, v[132:133]
	v_lshlrev_b32_e32 v132, 4, v198
	v_cndmask_b32_e32 v5, v3, v5, vcc
	v_lshlrev_b32_e32 v162, 2, v5
	v_xor_b32_e32 v5, 32, v3
	v_cmp_lt_i32_e32 vcc, v5, v4
	s_mov_b64 s[0:1], 0xd000000
	s_mov_b32 s7, 0
	v_cndmask_b32_e32 v3, v3, v5, vcc
	v_lshl_add_u64 v[4:5], s[58:59], 0, v[132:133]
	v_lshl_add_u64 v[140:141], v[4:5], 0, s[0:1]
	v_readlane_b32 s1, v254, 6
	s_lshl_b32 s0, s14, 4
	s_lshl_b32 s1, s1, 1
	v_lshlrev_b32_e32 v1, 2, v1
	v_lshlrev_b32_e32 v163, 2, v3
	v_lshl_add_u64 v[142:143], s[22:23], 0, v[132:133]
	s_add_i32 s6, s0, s1
	s_lshl_b32 s76, s94, 4
	v_lshlrev_b32_e32 v132, 2, v130
	v_lshlrev_b32_e32 v164, 2, v2
	s_mov_b64 s[8:9], 0x200000
	s_mov_b64 s[24:25], 0x400000
	s_mov_b64 s[30:31], 0x600000
	s_mov_b64 s[36:37], 0x800000
	s_mov_b64 s[38:39], 0xa00000
	s_mov_b64 s[40:41], 0xc00000
	s_mov_b64 s[42:43], 0xe00000
	s_mov_b64 s[44:45], 0x200800
	s_mov_b64 s[46:47], 0x400800
	s_mov_b64 s[48:49], 0x600800
	s_mov_b64 s[52:53], 0x800800
	s_mov_b64 s[54:55], 0xa00800
	s_mov_b64 s[64:65], 0xc00800
	s_mov_b64 s[66:67], 0xe00800
	v_mov_b32_e32 v165, 0x358637bd
	s_mov_b32 s77, 0xf800000
	v_mov_b32_e32 v166, 0x260
	s_branch .LBB0_594
